# attention loops: 68 packed v_pk_add_f32 (s - m) beside the MFMAs split into scalar v_sub_f32 pairs (bit-identical)
# baseline (speedup 1.0000x reference)
.LBB0_857:
	ds_read_b128 v[64:67], v197
	ds_read_b128 v[100:103], v197 offset:32
	ds_read_b128 v[148:151], v197 offset:128
	ds_read_b128 v[68:71], v197 offset:160
	ds_read_b128 v[104:107], v197 offset:64
	ds_read_b128 v[108:111], v197 offset:96
	ds_read_b128 v[72:75], v197 offset:192
	ds_read_b128 v[76:79], v197 offset:224
	s_waitcnt lgkmcnt(14)
	v_mfma_f32_32x32x16_bf16 v[32:47], v[140:143], v[176:179], v[32:47]
	v_exp_f32_e32 v80, v80
	v_exp_f32_e32 v81, v81
	v_exp_f32_e32 v82, v82
	v_exp_f32_e32 v83, v83
	s_waitcnt lgkmcnt(7)
	v_sub_f32_e32 v96, v64, v196
	v_sub_f32_e32 v97, v65, v196
	v_sub_f32_e32 v98, v66, v196
	v_sub_f32_e32 v99, v67, v196
	s_waitcnt lgkmcnt(2)
	v_mfma_f32_32x32x16_bf16 v[16:31], v[140:143], v[172:175], v[16:31]
	v_exp_f32_e32 v84, v84
	v_exp_f32_e32 v85, v85
	v_exp_f32_e32 v86, v86
	v_exp_f32_e32 v87, v87
	v_sub_f32_e32 v100, v100, v196
	v_sub_f32_e32 v101, v101, v196
	v_sub_f32_e32 v102, v102, v196
	v_sub_f32_e32 v103, v103, v196
	s_nop 0
	v_add_u32_e32 v14, s20, v223
	ds_read_b128 v[180:183], v14
	ds_read_b128 v[144:147], v14 offset:512
	v_mfma_f32_32x32x16_bf16 v[32:47], v[136:139], v[168:171], v[32:47]
	v_exp_f32_e32 v88, v88
	v_exp_f32_e32 v89, v89
	v_exp_f32_e32 v90, v90
	v_exp_f32_e32 v91, v91
	v_sub_f32_e32 v104, v104, v196
	v_sub_f32_e32 v105, v105, v196
	v_sub_f32_e32 v106, v106, v196
	v_sub_f32_e32 v107, v107, v196
	s_nop 0
	ds_read_b128 v[176:179], v14 offset:2048
	ds_read_b128 v[152:155], v14 offset:2560
	v_mfma_f32_32x32x16_bf16 v[16:31], v[136:139], v[164:167], v[16:31]
	v_exp_f32_e32 v92, v92
	v_exp_f32_e32 v93, v93
	v_exp_f32_e32 v94, v94
	v_exp_f32_e32 v95, v95
	v_sub_f32_e32 v108, v108, v196
	v_sub_f32_e32 v109, v109, v196
	v_sub_f32_e32 v110, v110, v196
	v_sub_f32_e32 v111, v111, v196
	s_nop 0
	ds_read_b128 v[172:175], v14 offset:4096
	ds_read_b128 v[156:159], v14 offset:4608
	v_mfma_f32_32x32x16_bf16 v[32:47], v[132:135], v[160:163], v[32:47]
	v_exp_f32_e32 v48, v48
	v_exp_f32_e32 v49, v49
	v_exp_f32_e32 v50, v50
	v_exp_f32_e32 v51, v51
	v_sub_f32_e32 v64, v148, v196
	v_sub_f32_e32 v65, v149, v196
	v_sub_f32_e32 v66, v150, v196
	v_sub_f32_e32 v67, v151, v196
	s_waitcnt lgkmcnt(6)
	ds_read_b128 v[168:171], v14 offset:6144
	ds_read_b128 v[148:151], v14 offset:6656
	v_mfma_f32_32x32x16_bf16 v[16:31], v[132:135], v[10:13], v[16:31]
	v_exp_f32_e32 v52, v52
	v_exp_f32_e32 v53, v53
	v_exp_f32_e32 v54, v54
	v_exp_f32_e32 v55, v55
	v_sub_f32_e32 v68, v68, v196
	v_sub_f32_e32 v69, v69, v196
	v_sub_f32_e32 v70, v70, v196
	v_sub_f32_e32 v71, v71, v196
	s_nop 0
	v_mfma_f32_32x32x16_bf16 v[32:47], v[128:131], v[6:9], v[32:47]
	v_exp_f32_e32 v56, v56
	v_exp_f32_e32 v57, v57
	v_exp_f32_e32 v58, v58
	v_exp_f32_e32 v59, v59
	v_sub_f32_e32 v72, v72, v196
	v_sub_f32_e32 v73, v73, v196
	v_sub_f32_e32 v74, v74, v196
	v_sub_f32_e32 v75, v75, v196
	s_nop 0
	v_mfma_f32_32x32x16_bf16 v[16:31], v[128:131], v[2:5], v[16:31]
	v_exp_f32_e32 v60, v60
	v_exp_f32_e32 v61, v61
	v_exp_f32_e32 v62, v62
	v_exp_f32_e32 v63, v63
	v_sub_f32_e32 v76, v76, v196
	v_sub_f32_e32 v77, v77, v196
	v_sub_f32_e32 v78, v78, v196
	v_sub_f32_e32 v79, v79, v196
	s_nop 0
	s_waitcnt vmcnt(2) lgkmcnt(0)
	s_barrier
	s_andn2_b64 vcc, exec, s[14:15]
	s_cbranch_vccnz .LBB0_859
	s_waitcnt lgkmcnt(0)
	ds_read_b128 v[2:5], v217 offset:49248
	ds_read_b128 v[6:9], v217 offset:49216
	ds_read_b128 v[10:13], v217 offset:49184
	ds_read_b128 v[160:163], v217 offset:49152
	s_waitcnt lgkmcnt(3)
	v_pk_mul_f32 v[46:47], v[46:47], v[4:5]
	s_waitcnt lgkmcnt(2)
	v_pk_mul_f32 v[42:43], v[42:43], v[8:9]
	s_waitcnt lgkmcnt(1)
	v_pk_mul_f32 v[38:39], v[38:39], v[12:13]
	s_waitcnt lgkmcnt(0)
	v_pk_mul_f32 v[34:35], v[34:35], v[162:163]
	v_pk_mul_f32 v[44:45], v[44:45], v[2:3]
	v_pk_mul_f32 v[40:41], v[40:41], v[6:7]
	v_pk_mul_f32 v[36:37], v[36:37], v[10:11]
	v_pk_mul_f32 v[32:33], v[32:33], v[160:161]
	v_pk_mul_f32 v[30:31], v[30:31], v[4:5]
	v_pk_mul_f32 v[26:27], v[26:27], v[8:9]
	v_pk_mul_f32 v[22:23], v[22:23], v[12:13]
	v_pk_mul_f32 v[18:19], v[18:19], v[162:163]
	v_pk_mul_f32 v[28:29], v[28:29], v[2:3]
	v_pk_mul_f32 v[24:25], v[24:25], v[6:7]
	v_pk_mul_f32 v[20:21], v[20:21], v[10:11]
	v_pk_mul_f32 v[16:17], v[16:17], v[160:161]

.LBB0_860:
	ds_read_b128 v[48:51], v197 offset:256
	ds_read_b128 v[84:87], v197 offset:288
	ds_read_b128 v[176:179], v197 offset:384
	ds_read_b128 v[52:55], v197 offset:416
	ds_read_b128 v[88:91], v197 offset:320
	ds_read_b128 v[92:95], v197 offset:352
	ds_read_b128 v[56:59], v197 offset:448
	ds_read_b128 v[60:63], v197 offset:480
	s_waitcnt lgkmcnt(14)
	v_mfma_f32_32x32x16_bf16 v[32:47], v[140:143], v[184:187], v[32:47]
	v_exp_f32_e32 v96, v96
	v_exp_f32_e32 v97, v97
	v_exp_f32_e32 v98, v98
	v_exp_f32_e32 v99, v99
	s_waitcnt lgkmcnt(7)
	v_sub_f32_e32 v80, v48, v196
	v_sub_f32_e32 v81, v49, v196
	v_sub_f32_e32 v82, v50, v196
	v_sub_f32_e32 v83, v51, v196
	s_waitcnt lgkmcnt(2)
	v_mfma_f32_32x32x16_bf16 v[16:31], v[140:143], v[164:167], v[16:31]
	v_exp_f32_e32 v100, v100
	v_exp_f32_e32 v101, v101
	v_exp_f32_e32 v102, v102
	v_exp_f32_e32 v103, v103
	v_sub_f32_e32 v84, v84, v196
	v_sub_f32_e32 v85, v85, v196
	v_sub_f32_e32 v86, v86, v196
	v_sub_f32_e32 v87, v87, v196
	s_nop 0
	v_add_u32_e32 v0, s38, v223
	ds_read_b128 v[172:175], v0
	ds_read_b128 v[168:171], v0 offset:512
	v_mfma_f32_32x32x16_bf16 v[32:47], v[136:139], v[160:163], v[32:47]
	v_exp_f32_e32 v104, v104
	v_exp_f32_e32 v105, v105
	v_exp_f32_e32 v106, v106
	v_exp_f32_e32 v107, v107
	v_sub_f32_e32 v88, v88, v196
	v_sub_f32_e32 v89, v89, v196
	v_sub_f32_e32 v90, v90, v196
	v_sub_f32_e32 v91, v91, v196
	s_nop 0
	ds_read_b128 v[164:167], v0 offset:2048
	ds_read_b128 v[160:163], v0 offset:2560
	v_mfma_f32_32x32x16_bf16 v[16:31], v[136:139], v[144:147], v[16:31]
	v_exp_f32_e32 v108, v108
	v_exp_f32_e32 v109, v109
	v_exp_f32_e32 v110, v110
	v_exp_f32_e32 v111, v111
	v_sub_f32_e32 v92, v92, v196
	v_sub_f32_e32 v93, v93, v196
	v_sub_f32_e32 v94, v94, v196
	v_sub_f32_e32 v95, v95, v196
	s_nop 0
	ds_read_b128 v[156:159], v0 offset:4096
	ds_read_b128 v[148:151], v0 offset:4608
	v_mfma_f32_32x32x16_bf16 v[32:47], v[132:135], v[152:155], v[32:47]
	v_exp_f32_e32 v64, v64
	v_exp_f32_e32 v65, v65
	v_exp_f32_e32 v66, v66
	v_exp_f32_e32 v67, v67
	v_sub_f32_e32 v48, v176, v196
	v_sub_f32_e32 v49, v177, v196
	v_sub_f32_e32 v50, v178, v196
	v_sub_f32_e32 v51, v179, v196
	s_waitcnt lgkmcnt(6)
	ds_read_b128 v[152:155], v0 offset:6144
	ds_read_b128 v[144:147], v0 offset:6656
	v_mfma_f32_32x32x16_bf16 v[16:31], v[132:135], v[10:13], v[16:31]
	v_exp_f32_e32 v68, v68
	v_exp_f32_e32 v69, v69
	v_exp_f32_e32 v70, v70
	v_exp_f32_e32 v71, v71
	v_sub_f32_e32 v52, v52, v196
	v_sub_f32_e32 v53, v53, v196
	v_sub_f32_e32 v54, v54, v196
	v_sub_f32_e32 v55, v55, v196
	s_nop 0
	v_mfma_f32_32x32x16_bf16 v[32:47], v[128:131], v[6:9], v[32:47]
	v_exp_f32_e32 v72, v72
	v_exp_f32_e32 v73, v73
	v_exp_f32_e32 v74, v74
	v_exp_f32_e32 v75, v75
	v_sub_f32_e32 v56, v56, v196
	v_sub_f32_e32 v57, v57, v196
	v_sub_f32_e32 v58, v58, v196
	v_sub_f32_e32 v59, v59, v196
	s_nop 0
	v_mfma_f32_32x32x16_bf16 v[16:31], v[128:131], v[2:5], v[16:31]
	v_exp_f32_e32 v76, v76
	v_exp_f32_e32 v77, v77
	v_exp_f32_e32 v78, v78
	v_exp_f32_e32 v79, v79
	v_sub_f32_e32 v60, v60, v196
	v_sub_f32_e32 v61, v61, v196
	v_sub_f32_e32 v62, v62, v196
	v_sub_f32_e32 v63, v63, v196
	s_nop 0
	s_waitcnt vmcnt(2) lgkmcnt(0)
	s_barrier
	s_andn2_b64 vcc, exec, s[14:15]
	s_cbranch_vccnz .LBB0_862
	s_waitcnt lgkmcnt(0)
	ds_read_b128 v[2:5], v217 offset:49248
	ds_read_b128 v[6:9], v217 offset:49216
	ds_read_b128 v[10:13], v217 offset:49184
	ds_read_b128 v[176:179], v217 offset:49152
	s_waitcnt lgkmcnt(3)
	v_pk_mul_f32 v[46:47], v[46:47], v[4:5]
	s_waitcnt lgkmcnt(2)
	v_pk_mul_f32 v[42:43], v[42:43], v[8:9]
	s_waitcnt lgkmcnt(1)
	v_pk_mul_f32 v[38:39], v[38:39], v[12:13]
	s_waitcnt lgkmcnt(0)
	v_pk_mul_f32 v[34:35], v[34:35], v[178:179]
	v_pk_mul_f32 v[44:45], v[44:45], v[2:3]
	v_pk_mul_f32 v[40:41], v[40:41], v[6:7]
	v_pk_mul_f32 v[36:37], v[36:37], v[10:11]
	v_pk_mul_f32 v[32:33], v[32:33], v[176:177]
	v_pk_mul_f32 v[30:31], v[30:31], v[4:5]
	v_pk_mul_f32 v[26:27], v[26:27], v[8:9]
	v_pk_mul_f32 v[22:23], v[22:23], v[12:13]
	v_pk_mul_f32 v[18:19], v[18:19], v[178:179]
	v_pk_mul_f32 v[28:29], v[28:29], v[2:3]
	v_pk_mul_f32 v[24:25], v[24:25], v[6:7]
	v_pk_mul_f32 v[20:21], v[20:21], v[10:11]
	v_pk_mul_f32 v[16:17], v[16:17], v[176:177]

.LBB0_873:
	v_lshl_add_u32 v0, s36, 2, v220
	ds_read_b128 v[80:83], v0
	ds_read_b128 v[100:103], v0 offset:32
	ds_read_b128 v[112:115], v0 offset:128
	ds_read_b128 v[84:87], v0 offset:160
	ds_read_b128 v[104:107], v0 offset:64
	ds_read_b128 v[108:111], v0 offset:96
	ds_read_b128 v[88:91], v0 offset:192
	ds_read_b128 v[92:95], v0 offset:224
	s_waitcnt lgkmcnt(14)
	v_mfma_f32_32x32x16_bf16 v[32:47], v[140:143], v[176:179], v[32:47]
	v_exp_f32_e32 v64, v64
	v_exp_f32_e32 v65, v65
	v_exp_f32_e32 v66, v66
	v_exp_f32_e32 v67, v67
	s_waitcnt lgkmcnt(7)
	v_sub_f32_e32 v96, v80, v196
	v_sub_f32_e32 v97, v81, v196
	v_sub_f32_e32 v98, v82, v196
	v_sub_f32_e32 v99, v83, v196
	s_waitcnt lgkmcnt(2)
	v_mfma_f32_32x32x16_bf16 v[16:31], v[140:143], v[172:175], v[16:31]
	v_exp_f32_e32 v68, v68
	v_exp_f32_e32 v69, v69
	v_exp_f32_e32 v70, v70
	v_exp_f32_e32 v71, v71
	v_sub_f32_e32 v100, v100, v196
	v_sub_f32_e32 v101, v101, v196
	v_sub_f32_e32 v102, v102, v196
	v_sub_f32_e32 v103, v103, v196
	s_nop 0
	v_mfma_f32_32x32x16_bf16 v[32:47], v[136:139], v[168:171], v[32:47]
	v_exp_f32_e32 v72, v72
	v_exp_f32_e32 v73, v73
	v_exp_f32_e32 v74, v74
	v_exp_f32_e32 v75, v75
	v_sub_f32_e32 v104, v104, v196
	v_sub_f32_e32 v105, v105, v196
	v_sub_f32_e32 v106, v106, v196
	v_sub_f32_e32 v107, v107, v196
	s_nop 0
	v_mfma_f32_32x32x16_bf16 v[16:31], v[136:139], v[124:127], v[16:31]
	v_exp_f32_e32 v76, v76
	v_exp_f32_e32 v77, v77
	v_exp_f32_e32 v78, v78
	v_exp_f32_e32 v79, v79
	v_sub_f32_e32 v108, v108, v196
	v_sub_f32_e32 v109, v109, v196
	v_sub_f32_e32 v110, v110, v196
	v_sub_f32_e32 v111, v111, v196
	s_nop 0
	v_mfma_f32_32x32x16_bf16 v[32:47], v[132:135], v[120:123], v[32:47]
	v_exp_f32_e32 v48, v48
	v_exp_f32_e32 v49, v49
	v_exp_f32_e32 v50, v50
	v_exp_f32_e32 v51, v51
	v_sub_f32_e32 v80, v112, v196
	v_sub_f32_e32 v81, v113, v196
	v_sub_f32_e32 v82, v114, v196
	v_sub_f32_e32 v83, v115, v196
	s_waitcnt lgkmcnt(0)
	v_mfma_f32_32x32x16_bf16 v[16:31], v[132:135], v[10:13], v[16:31]
	v_exp_f32_e32 v52, v52
	v_exp_f32_e32 v53, v53
	v_exp_f32_e32 v54, v54
	v_exp_f32_e32 v55, v55
	v_sub_f32_e32 v84, v84, v196
	v_sub_f32_e32 v85, v85, v196
	v_sub_f32_e32 v86, v86, v196
	v_sub_f32_e32 v87, v87, v196
	s_nop 0
	v_mfma_f32_32x32x16_bf16 v[32:47], v[128:131], v[6:9], v[32:47]
	v_exp_f32_e32 v56, v56
	v_exp_f32_e32 v57, v57
	v_exp_f32_e32 v58, v58
	v_exp_f32_e32 v59, v59
	v_sub_f32_e32 v88, v88, v196
	v_sub_f32_e32 v89, v89, v196
	v_sub_f32_e32 v90, v90, v196
	v_sub_f32_e32 v91, v91, v196
	s_nop 0
	v_mfma_f32_32x32x16_bf16 v[16:31], v[128:131], v[2:5], v[16:31]
	v_exp_f32_e32 v60, v60
	v_exp_f32_e32 v61, v61
	v_exp_f32_e32 v62, v62
	v_exp_f32_e32 v63, v63
	v_sub_f32_e32 v92, v92, v196
	v_sub_f32_e32 v93, v93, v196
	v_sub_f32_e32 v94, v94, v196
	v_sub_f32_e32 v95, v95, v196
	s_nop 0
	s_andn2_b64 vcc, exec, s[2:3]
	s_cbranch_vccnz .LBB0_875
	s_waitcnt lgkmcnt(0)
	ds_read_b128 v[2:5], v217 offset:49248
	ds_read_b128 v[6:9], v217 offset:49216
	ds_read_b128 v[10:13], v217 offset:49184
	ds_read_b128 v[80:83], v217 offset:49152
	s_waitcnt lgkmcnt(3)
	v_pk_mul_f32 v[46:47], v[46:47], v[4:5]
	s_waitcnt lgkmcnt(2)
	v_pk_mul_f32 v[42:43], v[42:43], v[8:9]
	s_waitcnt lgkmcnt(1)
	v_pk_mul_f32 v[38:39], v[38:39], v[12:13]
	s_waitcnt lgkmcnt(0)
	v_pk_mul_f32 v[34:35], v[34:35], v[82:83]
	v_pk_mul_f32 v[44:45], v[44:45], v[2:3]
	v_pk_mul_f32 v[40:41], v[40:41], v[6:7]
	v_pk_mul_f32 v[36:37], v[36:37], v[10:11]
	v_pk_mul_f32 v[32:33], v[32:33], v[80:81]
	v_pk_mul_f32 v[30:31], v[30:31], v[4:5]
	v_pk_mul_f32 v[26:27], v[26:27], v[8:9]
	v_pk_mul_f32 v[22:23], v[22:23], v[12:13]
	v_pk_mul_f32 v[18:19], v[18:19], v[82:83]
	v_pk_mul_f32 v[28:29], v[28:29], v[2:3]
	v_pk_mul_f32 v[24:25], v[24:25], v[6:7]
	v_pk_mul_f32 v[20:21], v[20:21], v[10:11]
	v_pk_mul_f32 v[16:17], v[16:17], v[80:81]

.LBB0_888:
	ds_read_b128 v[64:67], v226
	ds_read_b128 v[100:103], v226 offset:32
	ds_read_b128 v[144:147], v226 offset:128
	ds_read_b128 v[68:71], v226 offset:160
	ds_read_b128 v[104:107], v226 offset:64
	ds_read_b128 v[108:111], v226 offset:96
	ds_read_b128 v[72:75], v226 offset:192
	ds_read_b128 v[76:79], v226 offset:224
	s_waitcnt lgkmcnt(14)
	v_mfma_f32_32x32x16_bf16 v[32:47], v[140:143], v[188:191], v[32:47]
	v_exp_f32_e32 v80, v80
	v_exp_f32_e32 v81, v81
	v_exp_f32_e32 v82, v82
	v_exp_f32_e32 v83, v83
	s_waitcnt lgkmcnt(7)
	v_sub_f32_e32 v96, v64, v196
	v_sub_f32_e32 v97, v65, v196
	v_sub_f32_e32 v98, v66, v196
	v_sub_f32_e32 v99, v67, v196
	s_waitcnt lgkmcnt(2)
	v_mfma_f32_32x32x16_bf16 v[16:31], v[140:143], v[172:175], v[16:31]
	v_exp_f32_e32 v84, v84
	v_exp_f32_e32 v85, v85
	v_exp_f32_e32 v86, v86
	v_exp_f32_e32 v87, v87
	v_sub_f32_e32 v100, v100, v196
	v_sub_f32_e32 v101, v101, v196
	v_sub_f32_e32 v102, v102, v196
	v_sub_f32_e32 v103, v103, v196
	s_nop 0
	v_add_u32_e32 v140, s39, v223
	ds_read_b128 v[172:175], v140
	ds_read_b128 v[168:171], v140 offset:512
	v_mfma_f32_32x32x16_bf16 v[32:47], v[136:139], v[184:187], v[32:47]
	v_exp_f32_e32 v88, v88
	v_exp_f32_e32 v89, v89
	v_exp_f32_e32 v90, v90
	v_exp_f32_e32 v91, v91
	v_sub_f32_e32 v104, v104, v196
	v_sub_f32_e32 v105, v105, v196
	v_sub_f32_e32 v106, v106, v196
	v_sub_f32_e32 v107, v107, v196
	s_nop 0
	ds_read_b128 v[164:167], v140 offset:2048
	ds_read_b128 v[160:163], v140 offset:2560
	v_mfma_f32_32x32x16_bf16 v[16:31], v[136:139], v[176:179], v[16:31]
	v_exp_f32_e32 v92, v92
	v_exp_f32_e32 v93, v93
	v_exp_f32_e32 v94, v94
	v_exp_f32_e32 v95, v95
	v_sub_f32_e32 v108, v108, v196
	v_sub_f32_e32 v109, v109, v196
	v_sub_f32_e32 v110, v110, v196
	v_sub_f32_e32 v111, v111, v196
	s_nop 0
	ds_read_b128 v[156:159], v140 offset:4096
	ds_read_b128 v[148:151], v140 offset:4608
	v_mfma_f32_32x32x16_bf16 v[32:47], v[132:135], v[180:183], v[32:47]
	v_exp_f32_e32 v48, v48
	v_exp_f32_e32 v49, v49
	v_exp_f32_e32 v50, v50
	v_exp_f32_e32 v51, v51
	v_sub_f32_e32 v64, v144, v196
	v_sub_f32_e32 v65, v145, v196
	v_sub_f32_e32 v66, v146, v196
	v_sub_f32_e32 v67, v147, v196
	s_waitcnt lgkmcnt(6)
	ds_read_b128 v[152:155], v140 offset:6144
	ds_read_b128 v[144:147], v140 offset:6656
	v_mfma_f32_32x32x16_bf16 v[16:31], v[132:135], v[10:13], v[16:31]
	v_exp_f32_e32 v52, v52
	v_exp_f32_e32 v53, v53
	v_exp_f32_e32 v54, v54
	v_exp_f32_e32 v55, v55
	v_sub_f32_e32 v68, v68, v196
	v_sub_f32_e32 v69, v69, v196
	v_sub_f32_e32 v70, v70, v196
	v_sub_f32_e32 v71, v71, v196
	s_nop 0
	v_mfma_f32_32x32x16_bf16 v[32:47], v[128:131], v[6:9], v[32:47]
	v_exp_f32_e32 v56, v56
	v_exp_f32_e32 v57, v57
	v_exp_f32_e32 v58, v58
	v_exp_f32_e32 v59, v59
	v_sub_f32_e32 v72, v72, v196
	v_sub_f32_e32 v73, v73, v196
	v_sub_f32_e32 v74, v74, v196
	v_sub_f32_e32 v75, v75, v196
	s_nop 0
	v_mfma_f32_32x32x16_bf16 v[16:31], v[128:131], v[2:5], v[16:31]
	v_exp_f32_e32 v60, v60
	v_exp_f32_e32 v61, v61
	v_exp_f32_e32 v62, v62
	v_exp_f32_e32 v63, v63
	v_sub_f32_e32 v76, v76, v196
	v_sub_f32_e32 v77, v77, v196
	v_sub_f32_e32 v78, v78, v196
	v_sub_f32_e32 v79, v79, v196
	s_nop 0
	s_mov_b64 s[18:19], -1
	s_and_b64 vcc, exec, s[16:17]
	s_cbranch_vccz .LBB0_921
	s_cmp_ge_u32 s21, s37
	s_cbranch_scc0 .LBB0_891
	s_waitcnt vmcnt(0) lgkmcnt(0)
	s_barrier
	s_mov_b64 s[18:19], 0

.LBB0_903:
	ds_read_b128 v[80:83], v226 offset:256
	ds_read_b128 v[84:87], v226 offset:288
	ds_read_b128 v[48:51], v226 offset:384
	ds_read_b128 v[52:55], v226 offset:416
	ds_read_b128 v[88:91], v226 offset:320
	ds_read_b128 v[92:95], v226 offset:352
	ds_read_b128 v[56:59], v226 offset:448
	ds_read_b128 v[60:63], v226 offset:480
	s_waitcnt lgkmcnt(14)
	v_mfma_f32_32x32x16_bf16 v[32:47], v[140:143], v[192:195], v[32:47]
	v_exp_f32_e32 v96, v96
	v_exp_f32_e32 v97, v97
	v_exp_f32_e32 v98, v98
	v_exp_f32_e32 v99, v99
	s_waitcnt lgkmcnt(7)
	v_sub_f32_e32 v80, v80, v196
	v_sub_f32_e32 v81, v81, v196
	v_sub_f32_e32 v82, v82, v196
	v_sub_f32_e32 v83, v83, v196
	s_waitcnt lgkmcnt(2)
	v_mfma_f32_32x32x16_bf16 v[16:31], v[140:143], v[188:191], v[16:31]
	v_exp_f32_e32 v100, v100
	v_exp_f32_e32 v101, v101
	v_exp_f32_e32 v102, v102
	v_exp_f32_e32 v103, v103
	v_sub_f32_e32 v84, v84, v196
	v_sub_f32_e32 v85, v85, v196
	v_sub_f32_e32 v86, v86, v196
	v_sub_f32_e32 v87, v87, v196
	s_nop 0
	v_cndmask_b32_e64 v140, 0, 1, s[22:23]
	v_cmp_ne_u32_e64 s[4:5], 1, v140
	s_andn2_b64 vcc, exec, s[22:23]
	v_add_u32_e32 v140, s38, v223
	s_cbranch_vccnz .LBB0_905
	ds_read_b128 v[172:175], v140
	ds_read_b128 v[168:171], v140 offset:512
